# attention V staging: wave w loads d-chunk w for key=lane so each V^T ds_write_b16 is 128 contiguous bytes (was 8-way bank conflicted)
# speedup vs baseline: 1.0067x; 1.0067x over previous
; __device__ __forceinline__ int lane_id() { int l = (int)__builtin_amdgcn_mbcnt_hi(~0u, __builtin_amdgcn_mbcnt_lo(~0u, 0u)); asm volatile("" : "+v"(l)); return l; }
; __device__ __forceinline__ void attn_phase(LAS unsigned char* lds, const int wid, const bf16_t* P, const float* LF, bf16_t* CAT, const float* qgain, const float* kgain) {
;     ...
;     float sbound;
;     {
;         float gq = fabsf(qgain[lane_id()]), gk = fabsf(kgain[lane_id()]);
; #pragma unroll
;         for (int o = 1; o < 64; o <<= 1) { gq = fmaxf(gq, __shfl_xor(gq, o)); gk = fmaxf(gk, __shfl_xor(gk, o)); }
;         sbound = 64.f * QSCALE * gq * gk * 1.03f + 40.f;
;     }
;     const int lane = lane_id(), tid = wid * 64 + lane, r32 = lane & 31, hh = lane >> 5;
;     const int ldkey = tid >> 3, ldd8 = (tid & 7) * 8;
.LBB0_242:
.LBB0_243:
	s_cmp_lt_i32 s36, 3
	s_cselect_b64 s[2:3], -1, 0
	s_cmp_gt_i32 s37, 2
	s_cselect_b64 s[4:5], -1, 0
	s_and_b64 s[2:3], s[2:3], s[4:5]
	s_andn2_b64 vcc, exec, s[2:3]
	s_cbranch_vccnz .LBB0_335
	v_mbcnt_hi_u32_b32 v140, -1, v254
	s_add_u32 s28, s0, 0x130
	s_addc_u32 s29, s1, 0
	v_mov_b32_e32 v0, v140
	s_add_i32 s2, 0, 0x20118
	v_mov_b32_e32 v2, s2
	ds_read_b64 v[0:1], v2
	v_mov_b32_e32 v4, v140
	v_xor_b32_e32 v6, 8, v140
	v_xor_b32_e32 v7, 16, v140
	v_xor_b32_e32 v8, 32, v140
	s_waitcnt lgkmcnt(0)
	v_readfirstlane_b32 s34, v0
	v_readfirstlane_b32 s35, v1
	ds_read_b64 v[0:1], v2
	s_add_u32 s38, s34, 0x9800000
	s_addc_u32 s39, s35, 0
	s_mov_b32 s41, 0
	s_waitcnt lgkmcnt(0)
	v_readfirstlane_b32 s2, v0
	v_readfirstlane_b32 s3, v1
	ds_read_b64 v[0:1], v2
	s_waitcnt lgkmcnt(0)
	v_readfirstlane_b32 s4, v0
	v_readfirstlane_b32 s5, v1
	s_add_u32 s30, s4, 0x1700000
	s_addc_u32 s31, s5, 0
	s_add_i32 s4, 0, 0x20040
	v_mov_b32_e32 v0, s4
	ds_read_b64 v[0:1], v0
	s_add_i32 s4, 0, 0x20048
	v_mov_b32_e32 v2, s4
	s_load_dword s23, s[0:1], 0x130
	s_cmpk_gt_i32 s22, 0xff
	s_waitcnt lgkmcnt(0)
	v_readfirstlane_b32 s4, v0
	v_readfirstlane_b32 s5, v1
	ds_read_b64 v[0:1], v2
	v_mov_b32_e32 v2, s4
	v_mov_b32_e32 v3, s5
	s_waitcnt lgkmcnt(0)
	v_readfirstlane_b32 s4, v0
	v_readfirstlane_b32 s5, v1
	s_nop 0
	v_ashrrev_i32_e32 v5, 31, v4
	v_lshl_add_u64 v[2:3], v[4:5], 2, v[2:3]
	flat_load_dword v4, v[2:3]
	v_mov_b32_e32 v2, v140
	v_mov_b32_e32 v0, s4
	v_mov_b32_e32 v1, s5
	v_xor_b32_e32 v5, 4, v140
	v_ashrrev_i32_e32 v3, 31, v2
	v_lshl_add_u64 v[0:1], v[2:3], 2, v[0:1]
	flat_load_dword v1, v[0:1]
	v_and_b32_e32 v0, 64, v140
	v_xor_b32_e32 v2, 1, v140
	v_add_u32_e32 v9, 64, v0
	v_xor_b32_e32 v3, 2, v140
	v_cmp_lt_i32_e32 vcc, v2, v9
	s_nop 1
	v_cndmask_b32_e32 v2, v140, v2, vcc
	v_cmp_lt_i32_e32 vcc, v3, v9
	v_lshlrev_b32_e32 v141, 2, v2
	s_waitcnt vmcnt(0) lgkmcnt(0)
	v_and_b32_e32 v2, 0x7fffffff, v4
	v_cndmask_b32_e32 v3, v140, v3, vcc
	v_lshlrev_b32_e32 v142, 2, v3
	ds_bpermute_b32 v2, v141, v2
	v_max_f32_e64 v3, |v4|, |v4|
	v_cmp_lt_i32_e32 vcc, v5, v9
	v_and_b32_e32 v4, 0x7fffffff, v1
	ds_bpermute_b32 v4, v141, v4
	s_waitcnt lgkmcnt(1)
	v_max_f32_e32 v2, v2, v2
	v_max_f32_e64 v1, |v1|, |v1|
	v_max_f32_e32 v2, v3, v2
	ds_bpermute_b32 v3, v142, v2
	s_waitcnt lgkmcnt(1)
	v_max_f32_e32 v4, v4, v4
	v_max_f32_e32 v1, v1, v4
	ds_bpermute_b32 v4, v142, v1
	v_cndmask_b32_e32 v5, v140, v5, vcc
	s_waitcnt lgkmcnt(1)
	v_max_f32_e32 v3, v3, v3
	v_lshlrev_b32_e32 v143, 2, v5
	v_max_f32_e32 v2, v2, v3
	s_waitcnt lgkmcnt(0)
	v_max_f32_e32 v4, v4, v4
	ds_bpermute_b32 v3, v143, v2
	v_max_f32_e32 v1, v1, v4
	ds_bpermute_b32 v4, v143, v1
	v_cmp_lt_i32_e32 vcc, v6, v9
	s_waitcnt lgkmcnt(1)
	v_max_f32_e32 v3, v3, v3
	v_cndmask_b32_e32 v6, v140, v6, vcc
	v_lshlrev_b32_e32 v144, 2, v6
	v_max_f32_e32 v2, v2, v3
	s_waitcnt lgkmcnt(0)
	v_max_f32_e32 v4, v4, v4
	ds_bpermute_b32 v3, v144, v2
	v_max_f32_e32 v1, v1, v4
	ds_bpermute_b32 v4, v144, v1
	v_cmp_lt_i32_e32 vcc, v7, v9
	s_waitcnt lgkmcnt(1)
	v_max_f32_e32 v3, v3, v3
	v_cndmask_b32_e32 v7, v140, v7, vcc
	v_lshlrev_b32_e32 v145, 2, v7
	v_max_f32_e32 v2, v2, v3
	s_waitcnt lgkmcnt(0)
	v_max_f32_e32 v4, v4, v4
	ds_bpermute_b32 v3, v145, v2
	v_max_f32_e32 v1, v1, v4
	ds_bpermute_b32 v4, v145, v1
	v_cmp_lt_i32_e32 vcc, v8, v9
	s_waitcnt lgkmcnt(1)
	v_max_f32_e32 v3, v3, v3
	v_cndmask_b32_e32 v5, v140, v8, vcc
	v_max_f32_e32 v3, v2, v3
	s_waitcnt lgkmcnt(0)
	v_max_f32_e32 v2, v4, v4
	v_lshlrev_b32_e32 v146, 2, v5
	v_max_f32_e32 v2, v1, v2
	ds_bpermute_b32 v5, v146, v3
	ds_bpermute_b32 v4, v146, v2
	v_mov_b32_e32 v1, v140
	s_nop 0
	v_lshl_add_u32 v147, s33, 6, v1
	s_cbranch_scc1 .LBB0_279
; __device__ __forceinline__ void attn_phase(LAS unsigned char* lds, const int wid, const bf16_t* P, const float* LF, bf16_t* CAT, const float* qgain, const float* kgain) {
;     ...
;     const int lane = lane_id(), tid = wid * 64 + lane, r32 = lane & 31, hh = lane >> 5;
;     const int ldkey = tid >> 3, ldd8 = (tid & 7) * 8;
;     for (int w = blockIdx.x; w < 256; w += gridDim.x) {
;         const int bh = w >> 2, jq = w & 3, b = bh >> 3, hd = bh & 7;
;         __syncthreads();
;         {
;             const f32x4 l0 = *(const GAS f32x4*)(LF + (size_t)bh * S + tid * 8), l1 = *(const GAS f32x4*)(LF + (size_t)bh * S + tid * 8 + 4);
;             float c[8]; c[0] = l0[0]; c[1] = c[0] + l0[1]; c[2] = c[1] + l0[2]; c[3] = c[2] + l0[3]; c[4] = c[3] + l1[0]; c[5] = c[4] + l1[1]; c[6] = c[5] + l1[2]; c[7] = c[6] + l1[3];
;             float inc = c[7];
; #pragma unroll
;             for (int o = 1; o < 64; o <<= 1) { const float t = __shfl_up(inc, o); if (lane >= o) inc += t; }
;             if (lane == 63) red[wid] = inc;
;             __syncthreads();
;             float base = inc - c[7];
;             for (int i = 0; i < wid; ++i) base += red[i];
; #pragma unroll
;             for (int i = 0; i < 8; ++i) CB[tid * 8 + i] = -(base + c[i]) * LOG2E;
;         }
;         __syncthreads();
;         const size_t tok0 = (size_t)b * S;
; #pragma unroll 1
;         for (int ui = 0; ui < 4; ++ui) {
;             const int qb = ui == 0 ? jq : (ui == 1 ? 15 - jq : (ui == 2 ? 7 - jq : 8 + jq));
;             const int q0 = qb * 256 + wid * 32, qrow = q0 + r32;
;             bf16x8 qf[4];
; #pragma unroll
;             for (int ds = 0; ds < 4; ++ds) qf[ds] = *(const GAS bf16x8*)(P + (tok0 + qrow) * NPROJ + hd * 64 + 16 * ds + 8 * hh);
;             f32x16 O[2];
; #pragma unroll
;             for (int i = 0; i < 16; ++i) { O[0][i] = 0.f; O[1][i] = 0.f; }
;             float mrun = -1e30f, lsum = 0.f;
;             unsigned done_w = 0u;
;             const int ntile = 4 * qb + 4;
;             u32x4 kreg, vreg;
;             {
;                 const size_t gk = (tok0 + (size_t)(ntile - 1) * 64 + ldkey) * NPROJ + hd * 64 + ldd8;
;                 kreg = *(const GAS u32x4*)(P + gk + 512); vreg = *(const GAS u32x4*)(P + gk + 1024);
;                 *(LAS u32x4*)(KB + ldkey * KPITCH + ldd8 * 2) = kreg;
;                 LAS unsigned char* vb = VB + ldd8 * VPITCH + ldkey * 2;
	v_add_u32_e32 v6, -1, v140
	v_cmp_lt_i32_e32 vcc, v6, v0
	v_max_f32_e32 v3, v3, v3
	v_max_f32_e32 v2, v2, v2
	v_cndmask_b32_e32 v6, v6, v140, vcc
	v_lshlrev_b32_e32 v148, 2, v6
	v_add_u32_e32 v6, -2, v140
	v_cmp_lt_i32_e32 vcc, v6, v0
	v_mov_b32_e32 v154, 0x42200000
	v_ashrrev_i32_e32 v7, 5, v1
	v_cndmask_b32_e32 v6, v6, v140, vcc
	v_lshlrev_b32_e32 v149, 2, v6
	v_add_u32_e32 v6, -4, v140
	v_cmp_lt_i32_e32 vcc, v6, v0
	s_lshl_b32 s4, s33, 2
	s_add_i32 s49, s4, 0
	v_cndmask_b32_e32 v6, v6, v140, vcc
	v_lshlrev_b32_e32 v150, 2, v6
	v_add_u32_e32 v6, -8, v140
	v_cmp_lt_i32_e32 vcc, v6, v0
	v_ashrrev_i32_e32 v104, 3, v147
	s_movk_i32 s4, 0x90
	v_cndmask_b32_e32 v6, v6, v140, vcc
	v_lshlrev_b32_e32 v151, 2, v6
	v_add_u32_e32 v6, -16, v140
	v_cmp_lt_i32_e32 vcc, v6, v0
	v_lshlrev_b32_e32 v159, 4, v7
	v_lshlrev_b32_e32 v112, 2, v7
	v_cndmask_b32_e32 v6, v6, v140, vcc
	v_lshlrev_b32_e32 v152, 2, v6
	v_subrev_u32_e32 v6, 32, v140
	v_cmp_lt_i32_e32 vcc, v6, v0
	s_cmp_gt_i32 s33, 0
	v_add_u32_e32 v160, 0, v159
	v_cndmask_b32_e32 v0, v6, v140, vcc
	v_lshlrev_b32_e32 v153, 2, v0
	s_waitcnt lgkmcnt(1)
	v_max_f32_e32 v0, v5, v5
	v_max_f32_e32 v0, v3, v0
	s_waitcnt lgkmcnt(0)
	v_max_f32_e32 v3, v4, v4
	v_max_f32_e32 v2, v2, v3
	v_mul_f32_e32 v0, 0x4138aa3b, v0
	v_lshlrev_b32_e32 v4, 3, v147
	v_mul_f32_e32 v0, v2, v0
	v_mov_b32_e32 v2, s2
	v_mov_b32_e32 v3, s3
	v_ashrrev_i32_e32 v5, 31, v4
	v_fmac_f32_e32 v154, 0x3f83d70a, v0
	v_lshlrev_b32_e32 v0, 3, v1
	v_lshl_add_u64 v[106:107], v[4:5], 2, v[2:3]
	v_lshlrev_b32_e32 v2, 3, v7
	v_and_b32_e32 v6, 56, v0
	v_ashrrev_i32_e32 v3, 31, v2
	v_mov_b32_e32 v0, 0
	v_lshl_add_u64 v[108:109], v[2:3], 1, s[38:39]
	v_lshlrev_b32_e32 v4, 1, v6
	v_mov_b32_e32 v5, v0
	v_mul_lo_u32 v3, v104, s4
	v_lshl_add_u64 v[110:111], s[38:39], 0, v[4:5]
	v_add3_u32 v157, 0, v3, v4
	v_mul_u32_u24_e32 v3, 0x88, v6
	v_lshlrev_b32_e32 v4, 1, v104
	v_ashrrev_i32_e32 v113, 31, v112
	s_cselect_b64 s[42:43], -1, 0
	s_lshl_b32 s62, s33, 5
	v_mov_b32_e32 v186, 0x440
	v_mul_u32_u24_e32 v186, s33, v186
	v_lshl_add_u32 v158, v1, 1, v186
	v_sub_u32_e32 v186, v1, v104
	v_mov_b32_e32 v187, 0x1400
	v_mul_lo_u32 v186, v186, v187
	v_lshlrev_b32_e32 v187, 1, v6
	v_sub_u32_e32 v186, v186, v187
	v_mov_b32_e32 v187, s33
	v_lshl_add_u32 v186, v187, 4, v186
	v_ashrrev_i32_e32 v187, 31, v186
	v_sub_u32_e32 v161, v160, v2
	s_and_b32 s63, s33, 7
	v_lshlrev_b64 v[2:3], 1, v[112:113]
	s_movk_i32 s65, 0x1400
	v_and_b32_e32 v155, 31, v1
	v_cmp_eq_u32_e64 s[2:3], 63, v1
	v_cmp_eq_u32_e64 s[4:5], 0, v1
	v_cmp_gt_i32_e64 s[6:7], 1, v1
	v_cmp_gt_i32_e64 s[8:9], 2, v1
	v_cmp_gt_i32_e64 s[10:11], 4, v1
	v_cmp_gt_i32_e64 s[12:13], 8, v1
	v_cmp_gt_i32_e64 s[14:15], 16, v1
	v_cmp_gt_i32_e64 s[16:17], 32, v1
	s_cmp_gt_u32 s33, 7
	v_lshl_add_u64 v[114:115], s[38:39], 0, v[2:3]
	v_lshl_add_u64 v[116:117], s[30:31], 0, v[2:3]
	v_mad_i64_i32 v[2:3], s[18:19], v104, s65, 0
	v_and_b32_e32 v1, 7, v1
	s_cselect_b64 s[44:45], -1, 0
	s_and_b32 s64, s33, 0x7ffffff8
	v_lshl_or_b32 v2, v1, 4, v2
	s_cmp_lg_u32 s63, 0
	v_lshl_add_u64 v[2:3], s[34:35], 0, v[2:3]
	s_mov_b64 s[18:19], 0x98a0800
	s_mov_b32 s50, 0xfffb0000
	v_lshl_add_u32 v156, v147, 5, 0
	v_ashrrev_i32_e32 v105, 31, v104
	v_mul_u32_u24_e32 v162, 0x90, v155
	v_mul_u32_u24_e32 v163, 0x88, v155
	s_cselect_b64 s[46:47], -1, 0
	v_lshl_add_u64 v[118:119], v[2:3], 0, s[18:19]
	s_add_i32 s66, 0, 0xcc00
	s_mov_b32 s48, 0xbfb8aa3b
	s_mov_b32 s67, 0xf149f2ca
	s_mov_b32 s51, -1
	v_mov_b32_e32 v113, 0x140000
	v_mov_b32_e32 v164, 0xf149f2ca
	s_mov_b32 s68, s22
	s_branch .LBB0_247

; #define LAS __attribute__((address_space(3)))
; #define GAS __attribute__((address_space(1)))
; __device__ __forceinline__ void attn_phase(LAS unsigned char* lds, const int wid, const bf16_t* P, const float* LF, bf16_t* CAT, const float* qgain, const float* kgain) {
;     ...
;         for (int ui = 0; ui < 4; ++ui) {
;             const int qb = ui == 0 ? jq : (ui == 1 ? 15 - jq : (ui == 2 ? 7 - jq : 8 + jq));
;             const int q0 = qb * 256 + wid * 32, qrow = q0 + r32;
;             bf16x8 qf[4];
; #pragma unroll
;             for (int ds = 0; ds < 4; ++ds) qf[ds] = *(const GAS bf16x8*)(P + (tok0 + qrow) * NPROJ + hd * 64 + 16 * ds + 8 * hh);
;             f32x16 O[2];
; #pragma unroll
;             for (int i = 0; i < 16; ++i) { O[0][i] = 0.f; O[1][i] = 0.f; }
;             float mrun = -1e30f, lsum = 0.f;
;             unsigned done_w = 0u;
;             const int ntile = 4 * qb + 4;
;             u32x4 kreg, vreg;
;             {
;                 const size_t gk = (tok0 + (size_t)(ntile - 1) * 64 + ldkey) * NPROJ + hd * 64 + ldd8;
;                 kreg = *(const GAS u32x4*)(P + gk + 512); vreg = *(const GAS u32x4*)(P + gk + 1024);
;                 *(LAS u32x4*)(KB + ldkey * KPITCH + ldd8 * 2) = kreg;
;                 LAS unsigned char* vb = VB + ldd8 * VPITCH + ldkey * 2;
;                 *(LAS bf16_t*)(vb + 0 * VPITCH) = (bf16_t)(vreg.x & 0xffff); *(LAS bf16_t*)(vb + 1 * VPITCH) = (bf16_t)(vreg.x >> 16);
;                 *(LAS bf16_t*)(vb + 2 * VPITCH) = (bf16_t)(vreg.y & 0xffff); *(LAS bf16_t*)(vb + 3 * VPITCH) = (bf16_t)(vreg.y >> 16);
;                 *(LAS bf16_t*)(vb + 4 * VPITCH) = (bf16_t)(vreg.z & 0xffff); *(LAS bf16_t*)(vb + 5 * VPITCH) = (bf16_t)(vreg.z >> 16);
;                 *(LAS bf16_t*)(vb + 6 * VPITCH) = (bf16_t)(vreg.w & 0xffff); *(LAS bf16_t*)(vb + 7 * VPITCH) = (bf16_t)(vreg.w >> 16);
;             }
;             __syncthreads();
; #pragma unroll 1
;             for (int it = 0; it < ntile; ++it) {
;                 const int kt = ntile - 1 - it, cb = it & 1;
;                 const bool more = it + 1 < ntile;
;                 if (more) {
;                     const size_t gk = (tok0 + (size_t)(kt - 1) * 64 + ldkey) * NPROJ + hd * 64 + ldd8;
;                     kreg = *(const GAS u32x4*)(P + gk + 512); vreg = *(const GAS u32x4*)(P + gk + 1024);
;                 }
.LBB0_264:
	s_lshl_b32 s75, s20, 2
	s_lshl_b32 s21, s20, 8
	s_or_b32 s40, s75, 3
	s_add_i32 s74, s21, s62
	s_lshl_b64 s[18:19], s[40:41], 6
	v_or_b32_e32 v134, s74, v155
	v_lshl_add_u64 v[2:3], s[18:19], 0, v[122:123]
	v_ashrrev_i32_e32 v135, 31, v134
	v_mad_u64_u32 v[4:5], s[18:19], v2, s65, v[124:125]
	v_lshl_add_u64 v[132:133], s[52:53], 0, v[134:135]
	v_mad_i32_i24 v5, v3, s65, v5
	v_mad_u64_u32 v[2:3], s[18:19], v132, s65, v[120:121]
	v_mad_i32_i24 v3, v133, s65, v3
	global_load_dwordx4 v[80:83], v[4:5], off offset:1024
	v_lshl_add_u64 v[188:189], v[4:5], 0, v[186:187]
	global_load_dwordx4 v[84:87], v[188:189], off offset:2048
	global_load_dwordx4 v[88:91], v[2:3], off
	global_load_dwordx4 v[92:95], v[2:3], off offset:32
	global_load_dwordx4 v[96:99], v[2:3], off offset:64
	global_load_dwordx4 v[100:103], v[2:3], off offset:96
	v_mad_u64_u32 v[136:137], s[18:19], s20, v113, v[130:131]
	s_lshl_b32 s18, s20, 10
	v_mov_b32_e32 v14, v0
	v_mov_b32_e32 v15, v0
	s_add_i32 s18, s18, 0
	v_mov_b32_e32 v1, v0
	v_mov_b32_e32 v2, v0
	v_mov_b32_e32 v3, v0
	v_mov_b32_e32 v4, v0
	v_mov_b32_e32 v5, v0
	v_mov_b32_e32 v6, v0
	v_mov_b32_e32 v7, v0
	v_mov_b32_e32 v8, v0
	v_mov_b32_e32 v9, v0
	v_mov_b32_e32 v10, v0
	v_mov_b32_e32 v11, v0
	v_mov_b32_e32 v12, v0
	v_mov_b32_e32 v13, v0
	v_mov_b64_e32 v[30:31], v[14:15]
	s_add_i32 s78, s18, 0x2fc
	v_mad_u64_u32 v[138:139], s[18:19], v132, s65, 0
	v_mov_b64_e32 v[46:47], v[14:15]
	s_mov_b32 s20, 0
	v_mov_b32_e32 v166, 0xf149f2ca
	v_mov_b32_e32 v135, 0
	v_mov_b32_e32 v165, 0
	s_add_i32 s75, s75, 4
	s_or_b32 s77, s21, 0xc0
	v_mov_b64_e32 v[28:29], v[12:13]
	v_mov_b64_e32 v[26:27], v[10:11]
	v_mov_b64_e32 v[24:25], v[8:9]
	v_mov_b64_e32 v[22:23], v[6:7]
	v_mov_b64_e32 v[20:21], v[4:5]
	v_mov_b64_e32 v[18:19], v[2:3]
	v_mov_b64_e32 v[16:17], v[0:1]
	s_or_b32 s76, s74, 31
	v_mad_i32_i24 v139, v133, s65, v139
	v_mov_b64_e32 v[44:45], v[12:13]
	v_mov_b64_e32 v[42:43], v[10:11]
	v_mov_b64_e32 v[40:41], v[8:9]
	v_mov_b64_e32 v[38:39], v[6:7]
	v_mov_b64_e32 v[36:37], v[4:5]
	v_mov_b64_e32 v[34:35], v[2:3]
	v_mov_b64_e32 v[32:33], v[0:1]
	s_waitcnt vmcnt(5)
	ds_write_b128 v157, v[80:83] offset:16384
	s_waitcnt vmcnt(4)
	ds_write_b16 v158, v84 offset:34816
	ds_write_b16_d16_hi v158, v84 offset:34952
	ds_write_b16 v158, v85 offset:35088
	ds_write_b16_d16_hi v158, v85 offset:35224
	ds_write_b16 v158, v86 offset:35360
	ds_write_b16_d16_hi v158, v86 offset:35496
	ds_write_b16 v158, v87 offset:35632
	ds_write_b16_d16_hi v158, v87 offset:35768
	s_waitcnt vmcnt(0) lgkmcnt(0)
	s_barrier
.LBB0_265:
	s_mov_b64 s[18:19], -1
	s_cmpk_eq_i32 s77, 0xffc0
	v_readfirstlane_b32 s79, v0
	v_readfirstlane_b32 s24, v0
	v_readfirstlane_b32 s21, v0
	s_cbranch_scc1 .LBB0_275
	s_add_i32 s79, s20, 1
	s_cmp_lt_u32 s79, s75
	s_cselect_b64 s[54:55], -1, 0
	s_cmp_ge_u32 s79, s75
	s_cbranch_scc1 .LBB0_268
	global_load_dwordx4 v[80:83], v[136:137], off offset:-1024
	v_lshl_add_u64 v[188:189], v[136:137], 0, v[186:187]
	global_load_dwordx4 v[84:87], v[188:189], off

; __device__ __forceinline__ int lane_id() { int l = (int)__builtin_amdgcn_mbcnt_hi(~0u, __builtin_amdgcn_mbcnt_lo(~0u, 0u)); asm volatile("" : "+v"(l)); return l; }
; __device__ __forceinline__ void attn_phase(LAS unsigned char* lds, const int wid, const bf16_t* P, const float* LF, bf16_t* CAT, const float* qgain, const float* kgain) {
;     ...
;     float sbound;
;     {
;         float gq = fabsf(qgain[lane_id()]), gk = fabsf(kgain[lane_id()]);
; #pragma unroll
;         for (int o = 1; o < 64; o <<= 1) { gq = fmaxf(gq, __shfl_xor(gq, o)); gk = fmaxf(gk, __shfl_xor(gk, o)); }
;         sbound = 64.f * QSCALE * gq * gk * 1.03f + 40.f;
;     }
;     const int lane = lane_id(), tid = wid * 64 + lane, r32 = lane & 31, hh = lane >> 5;
;     const int ldkey = tid >> 3, ldd8 = (tid & 7) * 8;
.LBB0_1874:
.LBB0_1875:
	s_cmp_lt_i32 s36, 19
	s_cselect_b64 s[2:3], -1, 0
	s_cmp_gt_i32 s37, 18
	s_cselect_b64 s[4:5], -1, 0
	s_and_b64 s[2:3], s[2:3], s[4:5]
	s_andn2_b64 vcc, exec, s[2:3]
	s_cbranch_vccnz .LBB0_1967
	v_mbcnt_hi_u32_b32 v140, -1, v254
	s_add_u32 s28, s0, 0x130
	s_addc_u32 s29, s1, 0
	s_waitcnt vmcnt(0)
	v_mov_b32_e32 v0, v140
	s_mov_b64 s[4:5], s[0:1]
	s_add_i32 s0, 0, 0x20118
	v_mov_b32_e32 v2, s0
	ds_read_b64 v[0:1], v2
	s_waitcnt lgkmcnt(0)
	v_mov_b32_e32 v4, v140
	v_xor_b32_e32 v6, 8, v140
	v_xor_b32_e32 v7, 16, v140
	v_xor_b32_e32 v8, 32, v140
	v_readfirstlane_b32 s34, v0
	v_readfirstlane_b32 s35, v1
	ds_read_b64 v[0:1], v2
	s_add_u32 s38, s34, 0x9800000
	s_addc_u32 s39, s35, 0
	s_mov_b32 s41, 0
	s_waitcnt lgkmcnt(0)
	v_readfirstlane_b32 s2, v0
	v_readfirstlane_b32 s3, v1
	ds_read_b64 v[0:1], v2
	s_waitcnt lgkmcnt(0)
	v_readfirstlane_b32 s0, v0
	v_readfirstlane_b32 s1, v1
	s_add_u32 s30, s0, 0x1700000
	s_addc_u32 s31, s1, 0
	s_add_i32 s0, 0, 0x20040
	v_mov_b32_e32 v0, s0
	ds_read_b64 v[0:1], v0
	s_add_i32 s0, 0, 0x20048
	v_mov_b32_e32 v2, s0
	s_load_dword s23, s[4:5], 0x130
	s_cmpk_gt_i32 s22, 0xff
	s_waitcnt lgkmcnt(0)
	v_readfirstlane_b32 s0, v0
	v_readfirstlane_b32 s1, v1
	ds_read_b64 v[0:1], v2
	v_mov_b32_e32 v2, s0
	v_mov_b32_e32 v3, s1
	s_waitcnt lgkmcnt(0)
	v_readfirstlane_b32 s0, v0
	v_readfirstlane_b32 s1, v1
	s_nop 0
	v_ashrrev_i32_e32 v5, 31, v4
	v_lshl_add_u64 v[2:3], v[4:5], 2, v[2:3]
	flat_load_dword v4, v[2:3] offset:256
	v_mov_b32_e32 v2, v140
	v_mov_b32_e32 v0, s0
	v_mov_b32_e32 v1, s1
	v_xor_b32_e32 v5, 4, v140
	v_ashrrev_i32_e32 v3, 31, v2
	v_lshl_add_u64 v[0:1], v[2:3], 2, v[0:1]
	flat_load_dword v1, v[0:1] offset:256
	v_and_b32_e32 v0, 64, v140
	v_xor_b32_e32 v2, 1, v140
	v_add_u32_e32 v9, 64, v0
	v_xor_b32_e32 v3, 2, v140
	v_cmp_lt_i32_e32 vcc, v2, v9
	s_nop 1
	v_cndmask_b32_e32 v2, v140, v2, vcc
	v_cmp_lt_i32_e32 vcc, v3, v9
	v_lshlrev_b32_e32 v141, 2, v2
	s_waitcnt vmcnt(0) lgkmcnt(0)
	v_and_b32_e32 v2, 0x7fffffff, v4
	v_cndmask_b32_e32 v3, v140, v3, vcc
	v_lshlrev_b32_e32 v142, 2, v3
	ds_bpermute_b32 v2, v141, v2
	v_max_f32_e64 v3, |v4|, |v4|
	v_cmp_lt_i32_e32 vcc, v5, v9
	v_and_b32_e32 v4, 0x7fffffff, v1
	ds_bpermute_b32 v4, v141, v4
	s_waitcnt lgkmcnt(1)
	v_max_f32_e32 v2, v2, v2
	v_max_f32_e64 v1, |v1|, |v1|
	v_max_f32_e32 v2, v3, v2
	ds_bpermute_b32 v3, v142, v2
	s_waitcnt lgkmcnt(1)
	v_max_f32_e32 v4, v4, v4
	v_max_f32_e32 v1, v1, v4
	ds_bpermute_b32 v4, v142, v1
	v_cndmask_b32_e32 v5, v140, v5, vcc
	s_waitcnt lgkmcnt(1)
	v_max_f32_e32 v3, v3, v3
	v_lshlrev_b32_e32 v143, 2, v5
	v_max_f32_e32 v2, v2, v3
	s_waitcnt lgkmcnt(0)
	v_max_f32_e32 v4, v4, v4
	ds_bpermute_b32 v3, v143, v2
	v_max_f32_e32 v1, v1, v4
	ds_bpermute_b32 v4, v143, v1
	v_cmp_lt_i32_e32 vcc, v6, v9
	s_waitcnt lgkmcnt(1)
	v_max_f32_e32 v3, v3, v3
	v_cndmask_b32_e32 v6, v140, v6, vcc
	v_lshlrev_b32_e32 v144, 2, v6
	v_max_f32_e32 v2, v2, v3
	s_waitcnt lgkmcnt(0)
	v_max_f32_e32 v4, v4, v4
	ds_bpermute_b32 v3, v144, v2
	v_max_f32_e32 v1, v1, v4
	ds_bpermute_b32 v4, v144, v1
	v_cmp_lt_i32_e32 vcc, v7, v9
	s_waitcnt lgkmcnt(1)
	v_max_f32_e32 v3, v3, v3
	v_cndmask_b32_e32 v7, v140, v7, vcc
	v_lshlrev_b32_e32 v145, 2, v7
	v_max_f32_e32 v2, v2, v3
	s_waitcnt lgkmcnt(0)
	v_max_f32_e32 v4, v4, v4
	ds_bpermute_b32 v3, v145, v2
	v_max_f32_e32 v1, v1, v4
	ds_bpermute_b32 v4, v145, v1
	v_cmp_lt_i32_e32 vcc, v8, v9
	s_waitcnt lgkmcnt(1)
	v_max_f32_e32 v3, v3, v3
	v_cndmask_b32_e32 v5, v140, v8, vcc
	v_max_f32_e32 v3, v2, v3
	s_waitcnt lgkmcnt(0)
	v_max_f32_e32 v2, v4, v4
	v_lshlrev_b32_e32 v146, 2, v5
	v_max_f32_e32 v2, v1, v2
	ds_bpermute_b32 v5, v146, v3
	ds_bpermute_b32 v4, v146, v2
	v_mov_b32_e32 v1, v140
	s_nop 0
	v_lshl_add_u32 v147, s33, 6, v1
	s_cbranch_scc1 .LBB0_1911
; __device__ __forceinline__ void attn_phase(LAS unsigned char* lds, const int wid, const bf16_t* P, const float* LF, bf16_t* CAT, const float* qgain, const float* kgain) {
;     ...
;     const int lane = lane_id(), tid = wid * 64 + lane, r32 = lane & 31, hh = lane >> 5;
;     const int ldkey = tid >> 3, ldd8 = (tid & 7) * 8;
;     for (int w = blockIdx.x; w < 256; w += gridDim.x) {
;         const int bh = w >> 2, jq = w & 3, b = bh >> 3, hd = bh & 7;
;         __syncthreads();
;         {
;             const f32x4 l0 = *(const GAS f32x4*)(LF + (size_t)bh * S + tid * 8), l1 = *(const GAS f32x4*)(LF + (size_t)bh * S + tid * 8 + 4);
;             float c[8]; c[0] = l0[0]; c[1] = c[0] + l0[1]; c[2] = c[1] + l0[2]; c[3] = c[2] + l0[3]; c[4] = c[3] + l1[0]; c[5] = c[4] + l1[1]; c[6] = c[5] + l1[2]; c[7] = c[6] + l1[3];
;             float inc = c[7];
; #pragma unroll
;             for (int o = 1; o < 64; o <<= 1) { const float t = __shfl_up(inc, o); if (lane >= o) inc += t; }
;             if (lane == 63) red[wid] = inc;
;             __syncthreads();
;             float base = inc - c[7];
;             for (int i = 0; i < wid; ++i) base += red[i];
; #pragma unroll
;             for (int i = 0; i < 8; ++i) CB[tid * 8 + i] = -(base + c[i]) * LOG2E;
;         }
;         __syncthreads();
;         const size_t tok0 = (size_t)b * S;
; #pragma unroll 1
;         for (int ui = 0; ui < 4; ++ui) {
;             const int qb = ui == 0 ? jq : (ui == 1 ? 15 - jq : (ui == 2 ? 7 - jq : 8 + jq));
;             const int q0 = qb * 256 + wid * 32, qrow = q0 + r32;
;             bf16x8 qf[4];
; #pragma unroll
;             for (int ds = 0; ds < 4; ++ds) qf[ds] = *(const GAS bf16x8*)(P + (tok0 + qrow) * NPROJ + hd * 64 + 16 * ds + 8 * hh);
;             f32x16 O[2];
; #pragma unroll
;             for (int i = 0; i < 16; ++i) { O[0][i] = 0.f; O[1][i] = 0.f; }
;             float mrun = -1e30f, lsum = 0.f;
;             unsigned done_w = 0u;
;             const int ntile = 4 * qb + 4;
;             u32x4 kreg, vreg;
;             {
;                 const size_t gk = (tok0 + (size_t)(ntile - 1) * 64 + ldkey) * NPROJ + hd * 64 + ldd8;
;                 kreg = *(const GAS u32x4*)(P + gk + 512); vreg = *(const GAS u32x4*)(P + gk + 1024);
;                 *(LAS u32x4*)(KB + ldkey * KPITCH + ldd8 * 2) = kreg;
;                 LAS unsigned char* vb = VB + ldd8 * VPITCH + ldkey * 2;
	v_add_u32_e32 v6, -1, v140
	v_cmp_lt_i32_e32 vcc, v6, v0
	v_max_f32_e32 v3, v3, v3
	v_max_f32_e32 v2, v2, v2
	v_cndmask_b32_e32 v6, v6, v140, vcc
	v_lshlrev_b32_e32 v148, 2, v6
	v_add_u32_e32 v6, -2, v140
	v_cmp_lt_i32_e32 vcc, v6, v0
	v_mov_b32_e32 v154, 0x42200000
	v_ashrrev_i32_e32 v7, 5, v1
	v_cndmask_b32_e32 v6, v6, v140, vcc
	v_lshlrev_b32_e32 v149, 2, v6
	v_add_u32_e32 v6, -4, v140
	v_cmp_lt_i32_e32 vcc, v6, v0
	s_lshl_b32 s0, s33, 2
	s_add_i32 s49, s0, 0
	v_cndmask_b32_e32 v6, v6, v140, vcc
	v_lshlrev_b32_e32 v150, 2, v6
	v_add_u32_e32 v6, -8, v140
	v_cmp_lt_i32_e32 vcc, v6, v0
	v_ashrrev_i32_e32 v104, 3, v147
	s_movk_i32 s0, 0x90
	v_cndmask_b32_e32 v6, v6, v140, vcc
	v_lshlrev_b32_e32 v151, 2, v6
	v_add_u32_e32 v6, -16, v140
	v_cmp_lt_i32_e32 vcc, v6, v0
	v_lshlrev_b32_e32 v159, 4, v7
	v_lshlrev_b32_e32 v112, 2, v7
	v_cndmask_b32_e32 v6, v6, v140, vcc
	v_lshlrev_b32_e32 v152, 2, v6
	v_subrev_u32_e32 v6, 32, v140
	v_cmp_lt_i32_e32 vcc, v6, v0
	s_cmp_gt_i32 s33, 0
	v_add_u32_e32 v160, 0, v159
	v_cndmask_b32_e32 v0, v6, v140, vcc
	v_lshlrev_b32_e32 v153, 2, v0
	s_waitcnt lgkmcnt(1)
	v_max_f32_e32 v0, v5, v5
	v_max_f32_e32 v0, v3, v0
	s_waitcnt lgkmcnt(0)
	v_max_f32_e32 v3, v4, v4
	v_max_f32_e32 v2, v2, v3
	v_mul_f32_e32 v0, 0x4138aa3b, v0
	v_lshlrev_b32_e32 v4, 3, v147
	v_mul_f32_e32 v0, v2, v0
	v_mov_b32_e32 v2, s2
	v_mov_b32_e32 v3, s3
	v_ashrrev_i32_e32 v5, 31, v4
	v_fmac_f32_e32 v154, 0x3f83d70a, v0
	v_lshlrev_b32_e32 v0, 3, v1
	v_lshl_add_u64 v[106:107], v[4:5], 2, v[2:3]
	v_lshlrev_b32_e32 v2, 3, v7
	v_and_b32_e32 v6, 56, v0
	v_ashrrev_i32_e32 v3, 31, v2
	v_mov_b32_e32 v0, 0
	v_lshl_add_u64 v[108:109], v[2:3], 1, s[38:39]
	v_lshlrev_b32_e32 v4, 1, v6
	v_mov_b32_e32 v5, v0
	v_mul_lo_u32 v3, v104, s0
	v_lshl_add_u64 v[110:111], s[38:39], 0, v[4:5]
	v_add3_u32 v157, 0, v3, v4
	v_mul_u32_u24_e32 v3, 0x88, v6
	v_lshlrev_b32_e32 v4, 1, v104
	v_ashrrev_i32_e32 v113, 31, v112
	s_cselect_b64 s[42:43], -1, 0
	s_lshl_b32 s62, s33, 5
	v_mov_b32_e32 v186, 0x440
	v_mul_u32_u24_e32 v186, s33, v186
	v_lshl_add_u32 v158, v1, 1, v186
	v_sub_u32_e32 v186, v1, v104
	v_mov_b32_e32 v187, 0x1400
	v_mul_lo_u32 v186, v186, v187
	v_lshlrev_b32_e32 v187, 1, v6
	v_sub_u32_e32 v186, v186, v187
	v_mov_b32_e32 v187, s33
	v_lshl_add_u32 v186, v187, 4, v186
	v_ashrrev_i32_e32 v187, 31, v186
	v_sub_u32_e32 v161, v160, v2
	s_and_b32 s63, s33, 7
	v_lshlrev_b64 v[2:3], 1, v[112:113]
	s_movk_i32 s65, 0x1400
	v_and_b32_e32 v155, 31, v1
	v_cmp_eq_u32_e64 s[2:3], 63, v1
	v_cmp_eq_u32_e64 s[4:5], 0, v1
	v_cmp_gt_i32_e64 s[6:7], 1, v1
	v_cmp_gt_i32_e64 s[8:9], 2, v1
	v_cmp_gt_i32_e64 s[10:11], 4, v1
	v_cmp_gt_i32_e64 s[12:13], 8, v1
	v_cmp_gt_i32_e64 s[14:15], 16, v1
	v_cmp_gt_i32_e64 s[16:17], 32, v1
	s_cmp_gt_u32 s33, 7
	v_lshl_add_u64 v[114:115], s[38:39], 0, v[2:3]
	v_lshl_add_u64 v[116:117], s[30:31], 0, v[2:3]
	v_mad_i64_i32 v[2:3], s[18:19], v104, s65, 0
	v_and_b32_e32 v1, 7, v1
	s_cselect_b64 s[44:45], -1, 0
	s_and_b32 s64, s33, 0x7ffffff8
	v_lshl_or_b32 v2, v1, 4, v2
	s_cmp_lg_u32 s63, 0
	v_lshl_add_u64 v[2:3], s[34:35], 0, v[2:3]
	s_mov_b64 s[18:19], 0x98a0800
	s_mov_b32 s50, 0xfffb0000
	v_lshl_add_u32 v156, v147, 5, 0
	v_ashrrev_i32_e32 v105, 31, v104
	v_mul_u32_u24_e32 v162, 0x90, v155
	v_mul_u32_u24_e32 v163, 0x88, v155
	s_cselect_b64 s[46:47], -1, 0
	v_lshl_add_u64 v[118:119], v[2:3], 0, s[18:19]
	s_add_i32 s66, 0, 0xcc00
	s_mov_b32 s48, 0xbfb8aa3b
	s_mov_b32 s67, 0xf149f2ca
	s_mov_b32 s51, -1
	v_mov_b32_e32 v113, 0x140000
	v_mov_b32_e32 v164, 0xf149f2ca
	s_mov_b32 s68, s22
	s_branch .LBB0_1879

; #define LAS __attribute__((address_space(3)))
; #define GAS __attribute__((address_space(1)))
; __device__ __forceinline__ void attn_phase(LAS unsigned char* lds, const int wid, const bf16_t* P, const float* LF, bf16_t* CAT, const float* qgain, const float* kgain) {
;     ...
;         for (int ui = 0; ui < 4; ++ui) {
;             const int qb = ui == 0 ? jq : (ui == 1 ? 15 - jq : (ui == 2 ? 7 - jq : 8 + jq));
;             const int q0 = qb * 256 + wid * 32, qrow = q0 + r32;
;             bf16x8 qf[4];
; #pragma unroll
;             for (int ds = 0; ds < 4; ++ds) qf[ds] = *(const GAS bf16x8*)(P + (tok0 + qrow) * NPROJ + hd * 64 + 16 * ds + 8 * hh);
;             f32x16 O[2];
; #pragma unroll
;             for (int i = 0; i < 16; ++i) { O[0][i] = 0.f; O[1][i] = 0.f; }
;             float mrun = -1e30f, lsum = 0.f;
;             unsigned done_w = 0u;
;             const int ntile = 4 * qb + 4;
;             u32x4 kreg, vreg;
;             {
;                 const size_t gk = (tok0 + (size_t)(ntile - 1) * 64 + ldkey) * NPROJ + hd * 64 + ldd8;
;                 kreg = *(const GAS u32x4*)(P + gk + 512); vreg = *(const GAS u32x4*)(P + gk + 1024);
;                 *(LAS u32x4*)(KB + ldkey * KPITCH + ldd8 * 2) = kreg;
;                 LAS unsigned char* vb = VB + ldd8 * VPITCH + ldkey * 2;
;                 *(LAS bf16_t*)(vb + 0 * VPITCH) = (bf16_t)(vreg.x & 0xffff); *(LAS bf16_t*)(vb + 1 * VPITCH) = (bf16_t)(vreg.x >> 16);
;                 *(LAS bf16_t*)(vb + 2 * VPITCH) = (bf16_t)(vreg.y & 0xffff); *(LAS bf16_t*)(vb + 3 * VPITCH) = (bf16_t)(vreg.y >> 16);
;                 *(LAS bf16_t*)(vb + 4 * VPITCH) = (bf16_t)(vreg.z & 0xffff); *(LAS bf16_t*)(vb + 5 * VPITCH) = (bf16_t)(vreg.z >> 16);
;                 *(LAS bf16_t*)(vb + 6 * VPITCH) = (bf16_t)(vreg.w & 0xffff); *(LAS bf16_t*)(vb + 7 * VPITCH) = (bf16_t)(vreg.w >> 16);
;             }
;             __syncthreads();
.LBB0_1896:
	s_lshl_b32 s75, s20, 2
	s_lshl_b32 s0, s20, 8
	s_or_b32 s40, s75, 3
	s_add_i32 s74, s0, s62
	s_lshl_b64 s[18:19], s[40:41], 6
	v_or_b32_e32 v134, s74, v155
	v_lshl_add_u64 v[2:3], s[18:19], 0, v[122:123]
	v_ashrrev_i32_e32 v135, 31, v134
	v_mad_u64_u32 v[4:5], s[18:19], v2, s65, v[124:125]
	v_lshl_add_u64 v[132:133], s[52:53], 0, v[134:135]
	v_mad_i32_i24 v5, v3, s65, v5
	v_mad_u64_u32 v[2:3], s[18:19], v132, s65, v[120:121]
	v_mad_i32_i24 v3, v133, s65, v3
	global_load_dwordx4 v[80:83], v[4:5], off offset:1024
	v_lshl_add_u64 v[188:189], v[4:5], 0, v[186:187]
	global_load_dwordx4 v[84:87], v[188:189], off offset:2048
	global_load_dwordx4 v[88:91], v[2:3], off
	global_load_dwordx4 v[92:95], v[2:3], off offset:32
	global_load_dwordx4 v[96:99], v[2:3], off offset:64
	global_load_dwordx4 v[100:103], v[2:3], off offset:96
	s_lshl_b32 s1, s20, 10
	v_mov_b32_e32 v14, v0
	v_mov_b32_e32 v15, v0
	v_mov_b32_e32 v1, v0
	v_mov_b32_e32 v2, v0
	v_mov_b32_e32 v3, v0
	v_mov_b32_e32 v4, v0
	v_mov_b32_e32 v5, v0
	v_mov_b32_e32 v6, v0
	v_mov_b32_e32 v7, v0
	v_mov_b32_e32 v8, v0
	v_mov_b32_e32 v9, v0
	v_mov_b32_e32 v10, v0
	v_mov_b32_e32 v11, v0
	v_mov_b32_e32 v12, v0
	v_mov_b32_e32 v13, v0
	s_add_i32 s1, s1, 0
	v_mov_b64_e32 v[30:31], v[14:15]
	v_mad_u64_u32 v[138:139], s[18:19], v132, s65, 0
	v_mov_b64_e32 v[46:47], v[14:15]
	v_mad_u64_u32 v[136:137], s[18:19], s20, v113, v[130:131]
	s_mov_b32 s20, 0
	v_mov_b32_e32 v166, 0xf149f2ca
	v_mov_b32_e32 v135, 0
	v_mov_b32_e32 v165, 0
	s_add_i32 s75, s75, 4
	s_or_b32 s77, s0, 0xc0
	v_mov_b64_e32 v[28:29], v[12:13]
	v_mov_b64_e32 v[26:27], v[10:11]
	v_mov_b64_e32 v[24:25], v[8:9]
	v_mov_b64_e32 v[22:23], v[6:7]
	v_mov_b64_e32 v[20:21], v[4:5]
	v_mov_b64_e32 v[18:19], v[2:3]
	v_mov_b64_e32 v[16:17], v[0:1]
	s_or_b32 s76, s74, 31
	s_add_i32 s78, s1, 0x2fc
	v_mad_i32_i24 v139, v133, s65, v139
	v_mov_b64_e32 v[44:45], v[12:13]
	v_mov_b64_e32 v[42:43], v[10:11]
	v_mov_b64_e32 v[40:41], v[8:9]
	v_mov_b64_e32 v[38:39], v[6:7]
	v_mov_b64_e32 v[36:37], v[4:5]
	v_mov_b64_e32 v[34:35], v[2:3]
	v_mov_b64_e32 v[32:33], v[0:1]
	s_waitcnt vmcnt(5)
	ds_write_b128 v157, v[80:83] offset:16384
	s_waitcnt vmcnt(4)
	ds_write_b16 v158, v84 offset:34816
	ds_write_b16_d16_hi v158, v84 offset:34952
	ds_write_b16 v158, v85 offset:35088
	ds_write_b16_d16_hi v158, v85 offset:35224
	ds_write_b16 v158, v86 offset:35360
	ds_write_b16_d16_hi v158, v86 offset:35496
	ds_write_b16 v158, v87 offset:35632
	ds_write_b16_d16_hi v158, v87 offset:35768
	s_waitcnt vmcnt(0) lgkmcnt(0)
	s_barrier
